# local_barrier: buffer_inv sc1 issued before the arrival atomic so the L1 invalidate overlaps arrival+poll
# speedup vs baseline: 1.0111x; 1.0111x over previous
; __device__ __forceinline__ unsigned xb_ld(unsigned* p)              { return __hip_atomic_load(p, __ATOMIC_RELAXED, __HIP_MEMORY_SCOPE_AGENT); }
; __device__ __forceinline__ void local_barrier(unsigned* ctl, unsigned x) {
;     asm volatile("s_waitcnt vmcnt(0)" ::: "memory");
;     __syncthreads();
;     if (threadIdx.x == 0) {
;         __builtin_amdgcn_s_waitcnt(0);
;         unsigned* cw = &ctl[XL_CNT(x)];
;         const unsigned old = l2_fetch_add(cw, 1u), target = (old / 32u + 1u) * 32u;
;         unsigned sp = 0;
;         while (l2_fetch_add(cw, 0u) < target) {
;             __builtin_amdgcn_s_sleep(1);
;             if ((++sp & 255u) == 0u) { if (xb_ld(&ctl[XB_TMO])) break; if (sp > XB_SPIN_CAP) { atomicAdd(&ctl[XB_TMO], 1u); break; } } }
.LBB0_189:
	v_readlane_b32 s0, v254, 51
	v_readlane_b32 s1, v254, 52
	s_andn2_b64 vcc, exec, s[0:1]
	s_nop 0
	v_cndmask_b32_e64 v0, 0, 1, s[0:1]
	v_cmp_ne_u32_e64 s[4:5], 1, v0
	s_mov_b64 s[0:1], -1
	s_cbranch_vccnz .LBB0_207
	s_waitcnt vmcnt(0)
	s_waitcnt vmcnt(0)
	s_barrier
	s_mov_b64 s[0:1], exec
	v_readlane_b32 s8, v252, 3
	v_readlane_b32 s9, v252, 4
	s_and_b64 s[8:9], s[0:1], s[8:9]
	s_mov_b64 exec, s[8:9]
	s_cbranch_execz .LBB0_206
	v_readlane_b32 s8, v252, 8
	v_readlane_b32 s9, v252, 9
	s_waitcnt vmcnt(0) expcnt(0) lgkmcnt(0)
	s_mov_b32 s24, 1
	v_mov_b64_e32 v[0:1], s[8:9]
	buffer_inv sc1
	global_atomic_add v2, v[0:1], v250, off sc0
	s_waitcnt vmcnt(0)
	s_mov_b64 s[8:9], 0
	v_and_b32_e32 v0, 0xffffffe0, v2
	v_add_u32_e32 v0, 32, v0
	s_branch .LBB0_194

; __device__ __forceinline__ void local_barrier(unsigned* ctl, unsigned x) {
;     ...
;         __builtin_amdgcn_fence(__ATOMIC_ACQUIRE, "agent");
;         asm volatile("s_waitcnt vmcnt(0)" ::: "memory");
;     }
;     __syncthreads();
.LBB0_205:
	s_or_b64 exec, exec, s[8:9]
	s_waitcnt vmcnt(0)
	s_waitcnt vmcnt(0)

; __device__ __forceinline__ unsigned xb_ld(unsigned* p)              { return __hip_atomic_load(p, __ATOMIC_RELAXED, __HIP_MEMORY_SCOPE_AGENT); }
; __device__ __forceinline__ void local_barrier(unsigned* ctl, unsigned x) {
;     asm volatile("s_waitcnt vmcnt(0)" ::: "memory");
;     __syncthreads();
;     if (threadIdx.x == 0) {
;         __builtin_amdgcn_s_waitcnt(0);
;         unsigned* cw = &ctl[XL_CNT(x)];
;         const unsigned old = l2_fetch_add(cw, 1u), target = (old / 32u + 1u) * 32u;
;         unsigned sp = 0;
;         while (l2_fetch_add(cw, 0u) < target) {
;             __builtin_amdgcn_s_sleep(1);
;             if ((++sp & 255u) == 0u) { if (xb_ld(&ctl[XB_TMO])) break; if (sp > XB_SPIN_CAP) { atomicAdd(&ctl[XB_TMO], 1u); break; } } }
.LBB0_323:
	s_waitcnt vmcnt(0)
	s_waitcnt vmcnt(0) lgkmcnt(0)
	s_barrier
	s_mov_b64 s[0:1], exec
	v_readlane_b32 s4, v252, 3
	v_readlane_b32 s5, v252, 4
	s_and_b64 s[4:5], s[0:1], s[4:5]
	s_mov_b64 exec, s[4:5]
	s_cbranch_execz .LBB0_339
	v_readlane_b32 s4, v252, 8
	v_readlane_b32 s5, v252, 9
	s_waitcnt vmcnt(0) expcnt(0) lgkmcnt(0)
	s_mov_b32 s20, 1
	v_mov_b64_e32 v[0:1], s[4:5]
	buffer_inv sc1
	global_atomic_add v2, v[0:1], v250, off sc0
	s_waitcnt vmcnt(0)
	s_mov_b64 s[4:5], 0
	v_and_b32_e32 v0, 0xffffffe0, v2
	v_add_u32_e32 v0, 32, v0
	s_branch .LBB0_327

; __device__ __forceinline__ void local_barrier(unsigned* ctl, unsigned x) {
;     ...
;         __builtin_amdgcn_fence(__ATOMIC_ACQUIRE, "agent");
;         asm volatile("s_waitcnt vmcnt(0)" ::: "memory");
;     }
;     __syncthreads();
.LBB0_338:
	s_or_b64 exec, exec, s[4:5]
	s_waitcnt vmcnt(0)
	s_waitcnt vmcnt(0)

; __device__ __forceinline__ unsigned xb_ld(unsigned* p)              { return __hip_atomic_load(p, __ATOMIC_RELAXED, __HIP_MEMORY_SCOPE_AGENT); }
; __device__ __forceinline__ void local_barrier(unsigned* ctl, unsigned x) {
;     asm volatile("s_waitcnt vmcnt(0)" ::: "memory");
;     __syncthreads();
;     if (threadIdx.x == 0) {
;         __builtin_amdgcn_s_waitcnt(0);
;         unsigned* cw = &ctl[XL_CNT(x)];
;         const unsigned old = l2_fetch_add(cw, 1u), target = (old / 32u + 1u) * 32u;
;         unsigned sp = 0;
;         while (l2_fetch_add(cw, 0u) < target) {
;             __builtin_amdgcn_s_sleep(1);
;             if ((++sp & 255u) == 0u) { if (xb_ld(&ctl[XB_TMO])) break; if (sp > XB_SPIN_CAP) { atomicAdd(&ctl[XB_TMO], 1u); break; } } }
.LBB0_514:
	v_readlane_b32 s0, v254, 51
	v_readlane_b32 s1, v254, 52
	s_andn2_b64 vcc, exec, s[0:1]
	s_nop 0
	v_cndmask_b32_e64 v0, 0, 1, s[0:1]
	v_cmp_ne_u32_e64 s[4:5], 1, v0
	s_mov_b64 s[0:1], -1
	s_nop 0
	v_writelane_b32 v255, s4, 0
	s_nop 1
	v_writelane_b32 v255, s5, 1
	s_cbranch_vccnz .LBB0_532
	s_waitcnt vmcnt(0)
	s_waitcnt lgkmcnt(0)
	s_barrier
	s_mov_b64 s[0:1], exec
	v_readlane_b32 s4, v252, 3
	v_readlane_b32 s5, v252, 4
	s_and_b64 s[4:5], s[0:1], s[4:5]
	s_mov_b64 exec, s[4:5]
	s_cbranch_execz .LBB0_531
	v_readlane_b32 s4, v252, 8
	v_readlane_b32 s5, v252, 9
	s_waitcnt vmcnt(0) expcnt(0) lgkmcnt(0)
	s_mov_b32 s20, 1
	v_mov_b64_e32 v[0:1], s[4:5]
	buffer_inv sc1
	global_atomic_add v2, v[0:1], v250, off sc0
	s_waitcnt vmcnt(0)
	s_mov_b64 s[4:5], 0
	v_and_b32_e32 v0, 0xffffffe0, v2
	v_add_u32_e32 v0, 32, v0
	s_branch .LBB0_519

; __device__ __forceinline__ unsigned xb_ld(unsigned* p)              { return __hip_atomic_load(p, __ATOMIC_RELAXED, __HIP_MEMORY_SCOPE_AGENT); }
; __device__ __forceinline__ void local_barrier(unsigned* ctl, unsigned x) {
;     asm volatile("s_waitcnt vmcnt(0)" ::: "memory");
;     __syncthreads();
;     if (threadIdx.x == 0) {
;         __builtin_amdgcn_s_waitcnt(0);
;         unsigned* cw = &ctl[XL_CNT(x)];
;         const unsigned old = l2_fetch_add(cw, 1u), target = (old / 32u + 1u) * 32u;
;         unsigned sp = 0;
;         while (l2_fetch_add(cw, 0u) < target) {
;             __builtin_amdgcn_s_sleep(1);
;             if ((++sp & 255u) == 0u) { if (xb_ld(&ctl[XB_TMO])) break; if (sp > XB_SPIN_CAP) { atomicAdd(&ctl[XB_TMO], 1u); break; } } }
.LBB0_803:
	v_readlane_b32 s0, v255, 0
	v_readlane_b32 s1, v255, 1
	s_and_b64 vcc, exec, s[0:1]
	s_mov_b64 s[0:1], -1
	s_cbranch_vccnz .LBB0_821
	s_waitcnt vmcnt(0)
	s_barrier
	s_mov_b64 s[0:1], exec
	v_readlane_b32 s4, v252, 3
	v_readlane_b32 s5, v252, 4
	s_and_b64 s[4:5], s[0:1], s[4:5]
	s_mov_b64 exec, s[4:5]
	s_cbranch_execz .LBB0_820
	v_readlane_b32 s4, v252, 8
	v_readlane_b32 s5, v252, 9
	s_waitcnt vmcnt(0) expcnt(0) lgkmcnt(0)
	s_mov_b32 s20, 1
	v_mov_b64_e32 v[0:1], s[4:5]
	buffer_inv sc1
	global_atomic_add v2, v[0:1], v250, off sc0
	s_waitcnt vmcnt(0)
	s_mov_b64 s[4:5], 0
	v_and_b32_e32 v0, 0xffffffe0, v2
	v_add_u32_e32 v0, 32, v0
	s_branch .LBB0_808

; __device__ __forceinline__ unsigned xb_ld(unsigned* p)              { return __hip_atomic_load(p, __ATOMIC_RELAXED, __HIP_MEMORY_SCOPE_AGENT); }
; __device__ __forceinline__ void local_barrier(unsigned* ctl, unsigned x) {
;     asm volatile("s_waitcnt vmcnt(0)" ::: "memory");
;     __syncthreads();
;     if (threadIdx.x == 0) {
;         __builtin_amdgcn_s_waitcnt(0);
;         unsigned* cw = &ctl[XL_CNT(x)];
;         const unsigned old = l2_fetch_add(cw, 1u), target = (old / 32u + 1u) * 32u;
;         unsigned sp = 0;
;         while (l2_fetch_add(cw, 0u) < target) {
;             __builtin_amdgcn_s_sleep(1);
;             if ((++sp & 255u) == 0u) { if (xb_ld(&ctl[XB_TMO])) break; if (sp > XB_SPIN_CAP) { atomicAdd(&ctl[XB_TMO], 1u); break; } } }
.LBB0_1188:
	v_readlane_b32 s0, v255, 0
	v_readlane_b32 s1, v255, 1
	s_and_b64 vcc, exec, s[0:1]
	s_mov_b64 s[0:1], -1
	s_cbranch_vccnz .LBB0_1206
	s_waitcnt vmcnt(0)
	s_waitcnt lgkmcnt(0)
	s_barrier
	s_mov_b64 s[0:1], exec
	v_readlane_b32 s4, v252, 3
	v_readlane_b32 s5, v252, 4
	s_and_b64 s[4:5], s[0:1], s[4:5]
	s_mov_b64 exec, s[4:5]
	s_cbranch_execz .LBB0_1205
	v_readlane_b32 s4, v252, 8
	v_readlane_b32 s5, v252, 9
	s_waitcnt vmcnt(0) expcnt(0) lgkmcnt(0)
	s_mov_b32 s20, 1
	v_mov_b64_e32 v[0:1], s[4:5]
	buffer_inv sc1
	global_atomic_add v2, v[0:1], v250, off sc0
	s_waitcnt vmcnt(0)
	s_mov_b64 s[4:5], 0
	v_and_b32_e32 v0, 0xffffffe0, v2
	v_add_u32_e32 v0, 32, v0
	s_branch .LBB0_1193
